# pool epilogue: 8 gate loads batched, per-step waits removed
# speedup vs baseline: 1.0031x; 1.0031x over previous
.LBB0_320:
	s_lshl_b32 s0, s48, 5
	s_ashr_i32 s1, s0, 31
	s_lshl_b64 s[0:1], s[0:1], 1
	v_lshl_add_u64 v[42:43], v[40:41], 0, s[0:1]
	global_load_dwordx2 v[206:207], v[42:43], off
	global_load_dwordx2 v[208:209], v[42:43], off offset:16
	global_load_dwordx2 v[210:211], v[42:43], off offset:32
	global_load_dwordx2 v[212:213], v[42:43], off offset:48
	global_load_dwordx2 v[214:215], v[42:43], off offset:64
	global_load_dwordx2 v[216:217], v[42:43], off offset:80
	global_load_dwordx2 v[218:219], v[42:43], off offset:96
	global_load_dwordx2 v[220:221], v[42:43], off offset:112
	v_lshl_add_u32 v0, s48, 7, v46
	ds_read_b128 v[48:51], v0
	ds_read_b128 v[34:37], v0 offset:32
	s_or_b32 s28, s23, 32
	s_ashr_i32 s29, s28, 31
	s_add_i32 s22, s22, 1
	s_waitcnt lgkmcnt(0)
	v_pk_mul_f32 v[18:19], v[18:19], v[48:49]
	v_pk_mul_f32 v[20:21], v[20:21], v[50:51]
	v_pk_mul_f32 v[22:23], v[22:23], v[34:35]
	v_pk_mul_f32 v[24:25], v[24:25], v[36:37]
	s_waitcnt vmcnt(0)
	v_mov_b32_e32 v44, v206
	v_mov_b32_e32 v45, v207
	v_lshlrev_b32_e32 v52, 16, v44
	v_and_b32_e32 v53, 0xffff0000, v44
	v_mul_f32_e32 v44, 0xbfb8aa3b, v52
	v_exp_f32_e32 v44, v44
	s_nop 0
	v_add_f32_e32 v44, 1.0, v44
	v_rcp_f32_e32 v54, v44
	v_mul_f32_e32 v44, 0xbfb8aa3b, v53
	v_exp_f32_e32 v44, v44
	s_nop 0
	v_add_f32_e32 v44, 1.0, v44
	v_rcp_f32_e32 v55, v44
	s_nop 0
	v_pk_mul_f32 v[48:49], v[54:55], v[52:53]
	s_nop 0
	v_pk_mul_f32 v[18:19], v[18:19], v[48:49]
	s_nop 0
	v_cvt_pk_bf16_f32 v44, v18, v19
	v_lshlrev_b32_e32 v18, 16, v45
	v_and_b32_e32 v19, 0xffff0000, v45
	v_mul_f32_e32 v45, 0xbfb8aa3b, v18
	v_exp_f32_e32 v45, v45
	s_nop 0
	v_add_f32_e32 v45, 1.0, v45
	v_rcp_f32_e32 v48, v45
	v_mul_f32_e32 v45, 0xbfb8aa3b, v19
	v_exp_f32_e32 v45, v45
	s_nop 0
	v_add_f32_e32 v45, 1.0, v45
	v_rcp_f32_e32 v49, v45
	s_nop 0
	v_pk_mul_f32 v[18:19], v[48:49], v[18:19]
	s_nop 0
	v_pk_mul_f32 v[18:19], v[20:21], v[18:19]
	s_nop 0
	v_cvt_pk_bf16_f32 v45, v18, v19
	v_lshl_add_u64 v[18:19], v[38:39], 0, s[0:1]
	global_store_dwordx2 v[18:19], v[44:45], off
	v_mov_b32_e32 v20, v208
	v_mov_b32_e32 v21, v209
	s_lshl_b64 s[0:1], s[28:29], 1
	v_lshlrev_b32_e32 v44, 16, v20
	v_and_b32_e32 v45, 0xffff0000, v20
	v_mul_f32_e32 v20, 0xbfb8aa3b, v44
	v_exp_f32_e32 v20, v20
	s_nop 0
	v_add_f32_e32 v20, 1.0, v20
	v_rcp_f32_e32 v48, v20
	v_mul_f32_e32 v20, 0xbfb8aa3b, v45
	v_exp_f32_e32 v20, v20
	s_nop 0
	v_add_f32_e32 v20, 1.0, v20
	v_rcp_f32_e32 v49, v20
	s_nop 0
	v_pk_mul_f32 v[34:35], v[48:49], v[44:45]
	s_nop 0
	v_pk_mul_f32 v[22:23], v[22:23], v[34:35]
	s_nop 0
	v_cvt_pk_bf16_f32 v20, v22, v23
	v_lshlrev_b32_e32 v22, 16, v21
	v_and_b32_e32 v23, 0xffff0000, v21
	v_mul_f32_e32 v21, 0xbfb8aa3b, v22
	v_exp_f32_e32 v21, v21
	s_nop 0
	v_add_f32_e32 v21, 1.0, v21
	v_rcp_f32_e32 v34, v21
	v_mul_f32_e32 v21, 0xbfb8aa3b, v23
	v_exp_f32_e32 v21, v21
	s_nop 0
	v_add_f32_e32 v21, 1.0, v21
	v_rcp_f32_e32 v35, v21
	s_nop 0
	v_pk_mul_f32 v[22:23], v[34:35], v[22:23]
	s_nop 0
	v_pk_mul_f32 v[22:23], v[24:25], v[22:23]
	s_nop 0
	v_cvt_pk_bf16_f32 v21, v22, v23
	global_store_dwordx2 v[18:19], v[20:21], off offset:16
	v_mov_b32_e32 v24, v210
	v_mov_b32_e32 v25, v211
	ds_read_b128 v[20:23], v0 offset:64
	s_waitcnt lgkmcnt(0)
	v_pk_mul_f32 v[20:21], v[26:27], v[20:21]
	v_pk_mul_f32 v[22:23], v[28:29], v[22:23]
	v_lshlrev_b32_e32 v34, 16, v24
	v_and_b32_e32 v35, 0xffff0000, v24
	v_mul_f32_e32 v24, 0xbfb8aa3b, v34
	v_exp_f32_e32 v24, v24
	s_nop 0
	v_add_f32_e32 v24, 1.0, v24
	v_rcp_f32_e32 v36, v24
	v_mul_f32_e32 v24, 0xbfb8aa3b, v35
	v_exp_f32_e32 v24, v24
	s_nop 0
	v_add_f32_e32 v24, 1.0, v24
	v_rcp_f32_e32 v37, v24
	v_lshlrev_b32_e32 v24, 16, v25
	v_and_b32_e32 v25, 0xffff0000, v25
	v_pk_mul_f32 v[26:27], v[36:37], v[34:35]
	s_nop 0
	v_pk_mul_f32 v[20:21], v[20:21], v[26:27]
	s_nop 0
	v_cvt_pk_bf16_f32 v20, v20, v21
	v_mul_f32_e32 v21, 0xbfb8aa3b, v24
	v_exp_f32_e32 v21, v21
	s_nop 0
	v_add_f32_e32 v21, 1.0, v21
	v_rcp_f32_e32 v26, v21
	v_mul_f32_e32 v21, 0xbfb8aa3b, v25
	v_exp_f32_e32 v21, v21
	s_nop 0
	v_add_f32_e32 v21, 1.0, v21
	v_rcp_f32_e32 v27, v21
	s_nop 0
	v_pk_mul_f32 v[24:25], v[26:27], v[24:25]
	s_nop 0
	v_pk_mul_f32 v[22:23], v[22:23], v[24:25]
	s_nop 0
	v_cvt_pk_bf16_f32 v21, v22, v23
	global_store_dwordx2 v[18:19], v[20:21], off offset:32
	v_mov_b32_e32 v24, v212
	v_mov_b32_e32 v25, v213
	ds_read_b128 v[20:23], v0 offset:96
	s_waitcnt lgkmcnt(0)
	v_pk_mul_f32 v[20:21], v[30:31], v[20:21]
	v_pk_mul_f32 v[22:23], v[32:33], v[22:23]
	v_lshlrev_b32_e32 v26, 16, v24
	v_mul_f32_e32 v0, 0xbfb8aa3b, v26
	v_exp_f32_e32 v0, v0
	v_and_b32_e32 v27, 0xffff0000, v24
	v_lshlrev_b32_e32 v24, 16, v25
	v_and_b32_e32 v25, 0xffff0000, v25
	v_add_f32_e32 v0, 1.0, v0
	v_rcp_f32_e32 v28, v0
	v_mul_f32_e32 v0, 0xbfb8aa3b, v27
	v_exp_f32_e32 v0, v0
	s_nop 0
	v_add_f32_e32 v0, 1.0, v0
	v_rcp_f32_e32 v29, v0
	v_mul_f32_e32 v0, 0xbfb8aa3b, v24
	v_exp_f32_e32 v0, v0
	v_pk_mul_f32 v[26:27], v[28:29], v[26:27]
	s_nop 0
	v_pk_mul_f32 v[20:21], v[20:21], v[26:27]
	v_add_f32_e32 v0, 1.0, v0
	v_rcp_f32_e32 v26, v0
	v_mul_f32_e32 v0, 0xbfb8aa3b, v25
	v_exp_f32_e32 v0, v0
	v_cvt_pk_bf16_f32 v20, v20, v21
	v_add_f32_e32 v0, 1.0, v0
	v_rcp_f32_e32 v27, v0
	v_lshl_add_u32 v0, s28, 2, v46
	v_pk_mul_f32 v[24:25], v[26:27], v[24:25]
	s_nop 0
	v_pk_mul_f32 v[22:23], v[22:23], v[24:25]
	s_nop 0
	v_cvt_pk_bf16_f32 v21, v22, v23
	global_store_dwordx2 v[18:19], v[20:21], off offset:48
	v_lshl_add_u64 v[18:19], v[40:41], 0, s[0:1]
	v_mov_b32_e32 v22, v214
	v_mov_b32_e32 v23, v215
	ds_read_b128 v[18:21], v0
	s_waitcnt lgkmcnt(0)
	v_pk_mul_f32 v[2:3], v[2:3], v[18:19]
	v_pk_mul_f32 v[4:5], v[4:5], v[20:21]
	v_lshlrev_b32_e32 v24, 16, v22
	v_mul_f32_e32 v0, 0xbfb8aa3b, v24
	v_exp_f32_e32 v0, v0
	v_and_b32_e32 v25, 0xffff0000, v22
	v_add_f32_e32 v0, 1.0, v0
	v_rcp_f32_e32 v26, v0
	v_mul_f32_e32 v0, 0xbfb8aa3b, v25
	v_exp_f32_e32 v0, v0
	s_nop 0
	v_add_f32_e32 v0, 1.0, v0
	v_rcp_f32_e32 v27, v0
	s_nop 0
	v_pk_mul_f32 v[18:19], v[26:27], v[24:25]
	s_nop 0
	v_pk_mul_f32 v[2:3], v[2:3], v[18:19]
	v_lshlrev_b32_e32 v18, 16, v23
	v_mul_f32_e32 v0, 0xbfb8aa3b, v18
	v_exp_f32_e32 v0, v0
	v_and_b32_e32 v19, 0xffff0000, v23
	v_cvt_pk_bf16_f32 v2, v2, v3
	v_add_f32_e32 v0, 1.0, v0
	v_rcp_f32_e32 v22, v0
	v_mul_f32_e32 v0, 0xbfb8aa3b, v19
	v_exp_f32_e32 v0, v0
	s_nop 0
	v_add_f32_e32 v0, 1.0, v0
	v_rcp_f32_e32 v23, v0
	s_nop 0
	v_pk_mul_f32 v[18:19], v[22:23], v[18:19]
	s_nop 0
	v_pk_mul_f32 v[4:5], v[4:5], v[18:19]
	s_nop 0
	v_cvt_pk_bf16_f32 v3, v4, v5
	v_lshl_add_u64 v[4:5], v[38:39], 0, s[0:1]
	s_or_b32 s0, s23, 40
	s_ashr_i32 s1, s0, 31
	s_lshl_b64 s[28:29], s[0:1], 1
	global_store_dwordx2 v[4:5], v[2:3], off
	v_lshl_add_u64 v[2:3], v[40:41], 0, s[28:29]
	v_mov_b32_e32 v18, v216
	v_mov_b32_e32 v19, v217
	v_lshl_add_u32 v0, s0, 2, v46
	ds_read_b128 v[2:5], v0
	s_waitcnt lgkmcnt(0)
	v_pk_mul_f32 v[2:3], v[6:7], v[2:3]
	v_pk_mul_f32 v[4:5], v[8:9], v[4:5]
	v_lshlrev_b32_e32 v20, 16, v18
	v_mul_f32_e32 v0, 0xbfb8aa3b, v20
	v_exp_f32_e32 v0, v0
	v_and_b32_e32 v21, 0xffff0000, v18
	v_add_f32_e32 v0, 1.0, v0
	v_rcp_f32_e32 v22, v0
	v_mul_f32_e32 v0, 0xbfb8aa3b, v21
	v_exp_f32_e32 v0, v0
	s_nop 0
	v_add_f32_e32 v0, 1.0, v0
	v_rcp_f32_e32 v23, v0
	s_nop 0
	v_pk_mul_f32 v[6:7], v[22:23], v[20:21]
	s_nop 0
	v_pk_mul_f32 v[2:3], v[2:3], v[6:7]
	v_lshlrev_b32_e32 v6, 16, v19
	v_mul_f32_e32 v0, 0xbfb8aa3b, v6
	v_exp_f32_e32 v0, v0
	v_and_b32_e32 v7, 0xffff0000, v19
	v_cvt_pk_bf16_f32 v2, v2, v3
	v_add_f32_e32 v0, 1.0, v0
	v_rcp_f32_e32 v18, v0
	v_mul_f32_e32 v0, 0xbfb8aa3b, v7
	v_exp_f32_e32 v0, v0
	s_nop 0
	v_add_f32_e32 v0, 1.0, v0
	v_rcp_f32_e32 v19, v0
	s_nop 0
	v_pk_mul_f32 v[6:7], v[18:19], v[6:7]
	s_nop 0
	v_pk_mul_f32 v[4:5], v[4:5], v[6:7]
	s_nop 0
	v_cvt_pk_bf16_f32 v3, v4, v5
	v_lshl_add_u64 v[4:5], v[38:39], 0, s[28:29]
	s_or_b32 s28, s23, 48
	s_ashr_i32 s29, s28, 31
	s_lshl_b64 s[0:1], s[28:29], 1
	global_store_dwordx2 v[4:5], v[2:3], off
	v_lshl_add_u64 v[2:3], v[40:41], 0, s[0:1]
	v_mov_b32_e32 v6, v218
	v_mov_b32_e32 v7, v219
	v_lshl_add_u32 v0, s28, 2, v46
	ds_read_b128 v[2:5], v0
	s_waitcnt lgkmcnt(0)
	v_pk_mul_f32 v[2:3], v[10:11], v[2:3]
	v_pk_mul_f32 v[4:5], v[12:13], v[4:5]
	v_lshlrev_b32_e32 v8, 16, v6
	v_mul_f32_e32 v0, 0xbfb8aa3b, v8
	v_exp_f32_e32 v0, v0
	v_and_b32_e32 v9, 0xffff0000, v6
	v_lshlrev_b32_e32 v6, 16, v7
	v_and_b32_e32 v7, 0xffff0000, v7
	v_add_f32_e32 v0, 1.0, v0
	v_rcp_f32_e32 v18, v0
	v_mul_f32_e32 v0, 0xbfb8aa3b, v9
	v_exp_f32_e32 v0, v0
	s_nop 0
	v_add_f32_e32 v0, 1.0, v0
	v_rcp_f32_e32 v19, v0
	v_mul_f32_e32 v0, 0xbfb8aa3b, v6
	v_exp_f32_e32 v0, v0
	v_pk_mul_f32 v[8:9], v[18:19], v[8:9]
	s_nop 0
	v_pk_mul_f32 v[2:3], v[2:3], v[8:9]
	v_add_f32_e32 v0, 1.0, v0
	v_rcp_f32_e32 v8, v0
	v_mul_f32_e32 v0, 0xbfb8aa3b, v7
	v_exp_f32_e32 v0, v0
	v_cvt_pk_bf16_f32 v2, v2, v3
	v_add_f32_e32 v0, 1.0, v0
	v_rcp_f32_e32 v9, v0
	s_nop 0
	v_pk_mul_f32 v[6:7], v[8:9], v[6:7]
	s_nop 0
	v_pk_mul_f32 v[4:5], v[4:5], v[6:7]
	s_nop 0
	v_cvt_pk_bf16_f32 v3, v4, v5
	v_lshl_add_u64 v[4:5], v[38:39], 0, s[0:1]
	s_or_b32 s0, s23, 56
	s_ashr_i32 s1, s0, 31
	s_lshl_b64 s[28:29], s[0:1], 1
	global_store_dwordx2 v[4:5], v[2:3], off
	v_lshl_add_u64 v[2:3], v[40:41], 0, s[28:29]
	v_mov_b32_e32 v6, v220
	v_mov_b32_e32 v7, v221
	v_lshl_add_u32 v0, s0, 2, v46
	ds_read_b128 v[2:5], v0
	s_cmp_eq_u32 s22, s67
	s_waitcnt lgkmcnt(0)
	v_pk_mul_f32 v[2:3], v[14:15], v[2:3]
	v_pk_mul_f32 v[4:5], v[16:17], v[4:5]
	v_lshlrev_b32_e32 v8, 16, v6
	v_mul_f32_e32 v0, 0xbfb8aa3b, v8
	v_exp_f32_e32 v0, v0
	v_and_b32_e32 v9, 0xffff0000, v6
	v_lshlrev_b32_e32 v6, 16, v7
	v_and_b32_e32 v7, 0xffff0000, v7
	v_add_f32_e32 v0, 1.0, v0
	v_rcp_f32_e32 v10, v0
	v_mul_f32_e32 v0, 0xbfb8aa3b, v9
	v_exp_f32_e32 v0, v0
	s_nop 0
	v_add_f32_e32 v0, 1.0, v0
	v_rcp_f32_e32 v11, v0
	v_mul_f32_e32 v0, 0xbfb8aa3b, v6
	v_exp_f32_e32 v0, v0
	v_pk_mul_f32 v[8:9], v[10:11], v[8:9]
	s_nop 0
	v_pk_mul_f32 v[2:3], v[2:3], v[8:9]
	v_add_f32_e32 v0, 1.0, v0
	v_rcp_f32_e32 v8, v0
	v_mul_f32_e32 v0, 0xbfb8aa3b, v7
	v_exp_f32_e32 v0, v0
	v_cvt_pk_bf16_f32 v2, v2, v3
	v_add_f32_e32 v0, 1.0, v0
	v_rcp_f32_e32 v9, v0
	s_nop 0
	v_pk_mul_f32 v[6:7], v[8:9], v[6:7]
	s_nop 0
	v_pk_mul_f32 v[4:5], v[4:5], v[6:7]
	s_nop 0
	v_cvt_pk_bf16_f32 v3, v4, v5
	v_lshl_add_u64 v[4:5], v[38:39], 0, s[28:29]
	global_store_dwordx2 v[4:5], v[2:3], off
	s_cbranch_scc1 .LBB0_426
